# item_mla_expand row-norm pre-pass: row loads de-serialised (q: two groups of 4 dwordx4 in flight instead of 4 load-wait iterations; kv: both batches issued together)
# speedup vs baseline: 1.0104x; 1.0104x over previous
.LBB0_538:
	s_and_b64 vcc, exec, s[0:1]
	s_cbranch_vccz .LBB0_631
	v_readlane_b32 s0, v250, 10
	s_add_i32 s0, s0, s51
	v_mov_b32_e32 v120, v222
	s_bfe_u32 s26, s0, 0xd0003
	s_lshl_b32 s0, s26, 15
	v_ashrrev_i32_e32 v114, 1, v120
	s_add_u32 s0, s39, s0
	v_ashrrev_i32_e32 v115, 31, v114
	s_addc_u32 s1, s40, 0
	v_and_b32_e32 v18, 1, v120
	v_lshlrev_b64 v[2:3], 8, v[114:115]
	v_lshl_add_u64 v[2:3], s[0:1], 0, v[2:3]
	v_lshlrev_b32_e32 v0, 7, v18
	v_lshl_add_u64 v[14:15], v[2:3], 0, v[0:1]
	s_barrier
	global_load_dwordx4 v[2:5], v[14:15], off offset:48
	global_load_dwordx4 v[6:9], v[14:15], off offset:32
	global_load_dwordx4 v[10:13], v[14:15], off offset:16
	global_load_dwordx4 v[20:23], v[14:15], off
	global_load_dwordx4 v[124:127], v[14:15], off offset:112
	global_load_dwordx4 v[128:131], v[14:15], off offset:96
	global_load_dwordx4 v[132:135], v[14:15], off offset:80
	global_load_dwordx4 v[136:139], v[14:15], off offset:64
	s_waitcnt vmcnt(4)
	v_and_b32_e32 v16, 0xffff0000, v20
	v_lshlrev_b32_e32 v0, 16, v20
	v_mul_f32_e32 v16, v16, v16
	v_and_b32_e32 v17, 0xffff0000, v21
	v_fmac_f32_e32 v16, v0, v0
	v_lshlrev_b32_e32 v0, 16, v21
	v_mul_f32_e32 v17, v17, v17
	v_fmac_f32_e32 v17, v0, v0
	v_add_f32_e32 v0, v17, v16
	v_and_b32_e32 v17, 0xffff0000, v22
	v_lshlrev_b32_e32 v16, 16, v22
	v_mul_f32_e32 v17, v17, v17
	v_fmac_f32_e32 v17, v16, v16
	v_add_f32_e32 v0, v17, v0
	v_and_b32_e32 v17, 0xffff0000, v23
	v_lshlrev_b32_e32 v16, 16, v23
	v_mul_f32_e32 v17, v17, v17
	v_fmac_f32_e32 v17, v16, v16
	v_lshlrev_b32_e32 v16, 16, v10
	v_and_b32_e32 v10, 0xffff0000, v10
	v_mul_f32_e32 v10, v10, v10
	v_add_f32_e32 v0, v17, v0
	v_fmac_f32_e32 v10, v16, v16
	v_add_f32_e32 v0, v10, v0
	v_lshlrev_b32_e32 v10, 16, v11
	v_and_b32_e32 v11, 0xffff0000, v11
	v_mul_f32_e32 v11, v11, v11
	v_fmac_f32_e32 v11, v10, v10
	v_add_f32_e32 v0, v11, v0
	v_and_b32_e32 v11, 0xffff0000, v12
	v_lshlrev_b32_e32 v10, 16, v12
	v_mul_f32_e32 v11, v11, v11
	v_fmac_f32_e32 v11, v10, v10
	v_add_f32_e32 v0, v11, v0
	v_and_b32_e32 v11, 0xffff0000, v13
	v_lshlrev_b32_e32 v10, 16, v13
	v_mul_f32_e32 v11, v11, v11
	v_fmac_f32_e32 v11, v10, v10
	v_lshlrev_b32_e32 v10, 16, v6
	v_and_b32_e32 v6, 0xffff0000, v6
	v_mul_f32_e32 v6, v6, v6
	v_add_f32_e32 v0, v11, v0
	v_fmac_f32_e32 v6, v10, v10
	v_add_f32_e32 v0, v6, v0
	v_lshlrev_b32_e32 v6, 16, v7
	v_and_b32_e32 v7, 0xffff0000, v7
	v_mul_f32_e32 v7, v7, v7
	v_fmac_f32_e32 v7, v6, v6
	v_add_f32_e32 v0, v7, v0
	v_and_b32_e32 v7, 0xffff0000, v8
	v_lshlrev_b32_e32 v6, 16, v8
	v_mul_f32_e32 v7, v7, v7
	v_fmac_f32_e32 v7, v6, v6
	v_add_f32_e32 v0, v7, v0
	v_and_b32_e32 v7, 0xffff0000, v9
	v_lshlrev_b32_e32 v6, 16, v9
	v_mul_f32_e32 v7, v7, v7
	v_fmac_f32_e32 v7, v6, v6
	v_lshlrev_b32_e32 v6, 16, v2
	v_and_b32_e32 v2, 0xffff0000, v2
	v_mul_f32_e32 v2, v2, v2
	v_add_f32_e32 v0, v7, v0
	v_fmac_f32_e32 v2, v6, v6
	v_add_f32_e32 v0, v2, v0
	v_lshlrev_b32_e32 v2, 16, v3
	v_and_b32_e32 v3, 0xffff0000, v3
	v_mul_f32_e32 v3, v3, v3
	v_fmac_f32_e32 v3, v2, v2
	v_add_f32_e32 v0, v3, v0
	v_and_b32_e32 v3, 0xffff0000, v4
	v_lshlrev_b32_e32 v2, 16, v4
	v_mul_f32_e32 v3, v3, v3
	v_fmac_f32_e32 v3, v2, v2
	v_add_f32_e32 v0, v3, v0
	v_and_b32_e32 v3, 0xffff0000, v5
	v_lshlrev_b32_e32 v2, 16, v5
	v_mul_f32_e32 v3, v3, v3
	v_fmac_f32_e32 v3, v2, v2
	v_add_f32_e32 v0, v3, v0
	s_nop 0
	s_waitcnt vmcnt(0)
	v_lshlrev_b32_e32 v19, 16, v136
	v_and_b32_e32 v14, 0xffff0000, v136
	v_mul_f32_e32 v14, v14, v14
	v_fmac_f32_e32 v14, v19, v19
	v_add_f32_e32 v0, v14, v0
	v_lshlrev_b32_e32 v14, 16, v137
	v_and_b32_e32 v15, 0xffff0000, v137
	v_mul_f32_e32 v15, v15, v15
	v_fmac_f32_e32 v15, v14, v14
	v_add_f32_e32 v0, v15, v0
	v_and_b32_e32 v15, 0xffff0000, v138
	v_lshlrev_b32_e32 v14, 16, v138
	v_mul_f32_e32 v15, v15, v15
	v_fmac_f32_e32 v15, v14, v14
	v_add_f32_e32 v0, v15, v0
	v_and_b32_e32 v15, 0xffff0000, v139
	v_lshlrev_b32_e32 v14, 16, v139
	v_mul_f32_e32 v15, v15, v15
	v_fmac_f32_e32 v15, v14, v14
	v_lshlrev_b32_e32 v14, 16, v132
	v_and_b32_e32 v10, 0xffff0000, v132
	v_mul_f32_e32 v10, v10, v10
	v_add_f32_e32 v0, v15, v0
	v_fmac_f32_e32 v10, v14, v14
	v_add_f32_e32 v0, v10, v0
	v_lshlrev_b32_e32 v10, 16, v133
	v_and_b32_e32 v11, 0xffff0000, v133
	v_mul_f32_e32 v11, v11, v11
	v_fmac_f32_e32 v11, v10, v10
	v_add_f32_e32 v0, v11, v0
	v_and_b32_e32 v11, 0xffff0000, v134
	v_lshlrev_b32_e32 v10, 16, v134
	v_mul_f32_e32 v11, v11, v11
	v_fmac_f32_e32 v11, v10, v10
	v_add_f32_e32 v0, v11, v0
	v_and_b32_e32 v11, 0xffff0000, v135
	v_lshlrev_b32_e32 v10, 16, v135
	v_mul_f32_e32 v11, v11, v11
	v_fmac_f32_e32 v11, v10, v10
	v_lshlrev_b32_e32 v10, 16, v128
	v_and_b32_e32 v6, 0xffff0000, v128
	v_mul_f32_e32 v6, v6, v6
	v_add_f32_e32 v0, v11, v0
	v_fmac_f32_e32 v6, v10, v10
	v_add_f32_e32 v0, v6, v0
	v_lshlrev_b32_e32 v6, 16, v129
	v_and_b32_e32 v7, 0xffff0000, v129
	v_mul_f32_e32 v7, v7, v7
	v_fmac_f32_e32 v7, v6, v6
	v_add_f32_e32 v0, v7, v0
	v_and_b32_e32 v7, 0xffff0000, v130
	v_lshlrev_b32_e32 v6, 16, v130
	v_mul_f32_e32 v7, v7, v7
	v_fmac_f32_e32 v7, v6, v6
	v_add_f32_e32 v0, v7, v0
	v_and_b32_e32 v7, 0xffff0000, v131
	v_lshlrev_b32_e32 v6, 16, v131
	v_mul_f32_e32 v7, v7, v7
	v_fmac_f32_e32 v7, v6, v6
	v_lshlrev_b32_e32 v6, 16, v124
	v_and_b32_e32 v2, 0xffff0000, v124
	v_mul_f32_e32 v2, v2, v2
	v_add_f32_e32 v0, v7, v0
	v_fmac_f32_e32 v2, v6, v6
	v_add_f32_e32 v0, v2, v0
	v_lshlrev_b32_e32 v2, 16, v125
	v_and_b32_e32 v3, 0xffff0000, v125
	v_mul_f32_e32 v3, v3, v3
	v_fmac_f32_e32 v3, v2, v2
	v_add_f32_e32 v0, v3, v0
	v_and_b32_e32 v3, 0xffff0000, v126
	v_lshlrev_b32_e32 v2, 16, v126
	v_mul_f32_e32 v3, v3, v3
	v_fmac_f32_e32 v3, v2, v2
	v_add_f32_e32 v0, v3, v0
	v_and_b32_e32 v3, 0xffff0000, v127
	v_lshlrev_b32_e32 v2, 16, v127
	v_mul_f32_e32 v3, v3, v3
	v_fmac_f32_e32 v3, v2, v2
	v_add_f32_e32 v0, v3, v0
	v_and_b32_e32 v3, 64, v228
	v_xor_b32_e32 v2, 1, v228
	v_add_u32_e32 v3, 64, v3
	v_cmp_lt_i32_e32 vcc, v2, v3
	s_nop 1
	v_cndmask_b32_e32 v2, v228, v2, vcc
	v_lshlrev_b32_e32 v2, 2, v2
	ds_bpermute_b32 v2, v2, v0
	v_cmp_eq_u32_e32 vcc, 0, v18
	s_and_saveexec_b64 s[4:5], vcc
	s_cbranch_execz .LBB0_541
	s_waitcnt lgkmcnt(0)
	v_add_f32_e32 v0, v0, v2
	v_fmamk_f32 v0, v0, 0x3c000000, v224
	v_mul_f32_e32 v2, 0x4b800000, v0
	v_cmp_gt_f32_e32 vcc, s59, v0
	s_nop 1
	v_cndmask_b32_e32 v0, v0, v2, vcc
	v_rsq_f32_e32 v0, v0
	s_nop 0
	v_mul_f32_e32 v2, 0x45800000, v0
	v_cndmask_b32_e32 v0, v0, v2, vcc
	v_mov_b32_e32 v2, 0x12000
	v_lshl_add_u32 v2, v114, 2, v2
	ds_write_b32 v2, v0

.LBB0_591:
	v_readlane_b32 s0, v250, 11
	s_add_i32 s26, s51, s0
	s_add_i32 s26, s26, 0xfff8
	s_waitcnt vmcnt(10)
	v_mov_b32_e32 v86, v222
	s_and_b32 s0, s26, 0xffff
	s_mul_i32 s0, s0, 0xaaab
	v_ashrrev_i32_e32 v66, 1, v86
	s_lshr_b32 s27, s0, 18
	v_ashrrev_i32_e32 v67, 31, v66
	s_lshl_b32 s0, s27, 16
	s_mov_b32 s1, s81
	v_lshlrev_b64 v[2:3], 9, v[66:67]
	v_lshl_add_u64 v[2:3], s[0:1], 0, v[2:3]
	v_and_b32_e32 v0, 1, v86
	v_lshl_or_b32 v2, v0, 8, v2
	v_lshl_add_u64 v[2:3], s[20:21], 0, v[2:3]
	v_mov_b32_e32 v4, 0
	s_mov_b32 s1, -8
	s_barrier
	global_load_dwordx4 v[180:183], v[2:3], off offset:16
	global_load_dwordx4 v[184:187], v[2:3], off
	global_load_dwordx4 v[188:191], v[2:3], off offset:-16
	global_load_dwordx4 v[192:195], v[2:3], off offset:-32
	global_load_dwordx4 v[196:199], v[2:3], off offset:80
	global_load_dwordx4 v[200:203], v[2:3], off offset:64
	global_load_dwordx4 v[204:207], v[2:3], off offset:48
	global_load_dwordx4 v[236:239], v[2:3], off offset:32
	s_waitcnt vmcnt(4)
	v_lshlrev_b32_e32 v22, 16, v192
	v_and_b32_e32 v23, 0xffff0000, v192
	v_pk_mul_f32 v[22:23], v[22:23], v[22:23]
	s_nop 0
	v_add_f32_e32 v5, v22, v23
	v_and_b32_e32 v23, 0xffff0000, v194
	v_and_b32_e32 v22, 0xffff0000, v193
	v_add_f32_e32 v24, v4, v5
	v_lshlrev_b32_e32 v5, 16, v194
	v_lshlrev_b32_e32 v4, 16, v193
	v_pk_mul_f32 v[18:19], v[22:23], v[22:23]
	s_nop 0
	v_pk_fma_f32 v[4:5], v[4:5], v[4:5], v[18:19]
	v_and_b32_e32 v19, 0xffff0000, v190
	v_add_f32_e32 v4, v4, v24
	v_add_f32_e32 v18, v5, v4
	v_lshlrev_b32_e32 v4, 16, v195
	v_and_b32_e32 v5, 0xffff0000, v195
	v_pk_mul_f32 v[4:5], v[4:5], v[4:5]
	s_nop 0
	v_add_f32_e32 v4, v4, v5
	v_add_f32_e32 v18, v4, v18
	v_lshlrev_b32_e32 v4, 16, v188
	v_and_b32_e32 v5, 0xffff0000, v188
	v_pk_mul_f32 v[4:5], v[4:5], v[4:5]
	s_nop 0
	v_add_f32_e32 v4, v4, v5
	v_add_f32_e32 v20, v18, v4
	v_and_b32_e32 v18, 0xffff0000, v189
	v_lshlrev_b32_e32 v5, 16, v190
	v_lshlrev_b32_e32 v4, 16, v189
	v_pk_mul_f32 v[14:15], v[18:19], v[18:19]
	s_nop 0
	v_pk_fma_f32 v[4:5], v[4:5], v[4:5], v[14:15]
	v_and_b32_e32 v15, 0xffff0000, v186
	v_add_f32_e32 v4, v4, v20
	v_add_f32_e32 v14, v5, v4
	v_lshlrev_b32_e32 v4, 16, v191
	v_and_b32_e32 v5, 0xffff0000, v191
	v_pk_mul_f32 v[4:5], v[4:5], v[4:5]
	s_nop 0
	v_add_f32_e32 v4, v4, v5
	v_add_f32_e32 v14, v4, v14
	v_lshlrev_b32_e32 v4, 16, v184
	v_and_b32_e32 v5, 0xffff0000, v184
	v_pk_mul_f32 v[4:5], v[4:5], v[4:5]
	s_nop 0
	v_add_f32_e32 v4, v4, v5
	v_add_f32_e32 v16, v14, v4
	v_and_b32_e32 v14, 0xffff0000, v185
	v_lshlrev_b32_e32 v5, 16, v186
	v_lshlrev_b32_e32 v4, 16, v185
	v_pk_mul_f32 v[10:11], v[14:15], v[14:15]
	s_nop 0
	v_pk_fma_f32 v[4:5], v[4:5], v[4:5], v[10:11]
	v_and_b32_e32 v11, 0xffff0000, v182
	v_add_f32_e32 v4, v4, v16
	v_add_f32_e32 v10, v5, v4
	v_lshlrev_b32_e32 v4, 16, v187
	v_and_b32_e32 v5, 0xffff0000, v187
	v_pk_mul_f32 v[4:5], v[4:5], v[4:5]
	s_nop 0
	v_add_f32_e32 v4, v4, v5
	v_add_f32_e32 v10, v4, v10
	v_lshlrev_b32_e32 v4, 16, v180
	v_and_b32_e32 v5, 0xffff0000, v180
	v_pk_mul_f32 v[4:5], v[4:5], v[4:5]
	s_nop 0
	v_add_f32_e32 v4, v4, v5
	v_add_f32_e32 v12, v10, v4
	v_and_b32_e32 v10, 0xffff0000, v181
	v_lshlrev_b32_e32 v5, 16, v182
	v_lshlrev_b32_e32 v4, 16, v181
	v_pk_mul_f32 v[6:7], v[10:11], v[10:11]
	s_nop 0
	v_pk_fma_f32 v[4:5], v[4:5], v[4:5], v[6:7]
	s_nop 0
	v_add_f32_e32 v4, v4, v12
	v_add_f32_e32 v6, v5, v4
	v_lshlrev_b32_e32 v4, 16, v183
	v_and_b32_e32 v5, 0xffff0000, v183
	v_pk_mul_f32 v[4:5], v[4:5], v[4:5]
	s_nop 0
	v_add_f32_e32 v4, v4, v5
	v_add_f32_e32 v4, v4, v6
	global_load_dwordx4 v[180:183], v[2:3], off offset:144
	global_load_dwordx4 v[184:187], v[2:3], off offset:128
	global_load_dwordx4 v[188:191], v[2:3], off offset:112
	global_load_dwordx4 v[192:195], v[2:3], off offset:96
	s_waitcnt vmcnt(4)
	v_lshlrev_b32_e32 v22, 16, v236
	v_and_b32_e32 v23, 0xffff0000, v236
	v_pk_mul_f32 v[22:23], v[22:23], v[22:23]
	s_nop 0
	v_add_f32_e32 v5, v22, v23
	v_and_b32_e32 v23, 0xffff0000, v238
	v_and_b32_e32 v22, 0xffff0000, v237
	v_add_f32_e32 v24, v4, v5
	v_lshlrev_b32_e32 v5, 16, v238
	v_lshlrev_b32_e32 v4, 16, v237
	v_pk_mul_f32 v[18:19], v[22:23], v[22:23]
	s_nop 0
	v_pk_fma_f32 v[4:5], v[4:5], v[4:5], v[18:19]
	v_and_b32_e32 v19, 0xffff0000, v206
	v_add_f32_e32 v4, v4, v24
	v_add_f32_e32 v18, v5, v4
	v_lshlrev_b32_e32 v4, 16, v239
	v_and_b32_e32 v5, 0xffff0000, v239
	v_pk_mul_f32 v[4:5], v[4:5], v[4:5]
	s_nop 0
	v_add_f32_e32 v4, v4, v5
	v_add_f32_e32 v18, v4, v18
	v_lshlrev_b32_e32 v4, 16, v204
	v_and_b32_e32 v5, 0xffff0000, v204
	v_pk_mul_f32 v[4:5], v[4:5], v[4:5]
	s_nop 0
	v_add_f32_e32 v4, v4, v5
	v_add_f32_e32 v20, v18, v4
	v_and_b32_e32 v18, 0xffff0000, v205
	v_lshlrev_b32_e32 v5, 16, v206
	v_lshlrev_b32_e32 v4, 16, v205
	v_pk_mul_f32 v[14:15], v[18:19], v[18:19]
	s_nop 0
	v_pk_fma_f32 v[4:5], v[4:5], v[4:5], v[14:15]
	v_and_b32_e32 v15, 0xffff0000, v202
	v_add_f32_e32 v4, v4, v20
	v_add_f32_e32 v14, v5, v4
	v_lshlrev_b32_e32 v4, 16, v207
	v_and_b32_e32 v5, 0xffff0000, v207
	v_pk_mul_f32 v[4:5], v[4:5], v[4:5]
	s_nop 0
	v_add_f32_e32 v4, v4, v5
	v_add_f32_e32 v14, v4, v14
	v_lshlrev_b32_e32 v4, 16, v200
	v_and_b32_e32 v5, 0xffff0000, v200
	v_pk_mul_f32 v[4:5], v[4:5], v[4:5]
	s_nop 0
	v_add_f32_e32 v4, v4, v5
	v_add_f32_e32 v16, v14, v4
	v_and_b32_e32 v14, 0xffff0000, v201
	v_lshlrev_b32_e32 v5, 16, v202
	v_lshlrev_b32_e32 v4, 16, v201
	v_pk_mul_f32 v[10:11], v[14:15], v[14:15]
	s_nop 0
	v_pk_fma_f32 v[4:5], v[4:5], v[4:5], v[10:11]
	v_and_b32_e32 v11, 0xffff0000, v198
	v_add_f32_e32 v4, v4, v16
	v_add_f32_e32 v10, v5, v4
	v_lshlrev_b32_e32 v4, 16, v203
	v_and_b32_e32 v5, 0xffff0000, v203
	v_pk_mul_f32 v[4:5], v[4:5], v[4:5]
	s_nop 0
	v_add_f32_e32 v4, v4, v5
	v_add_f32_e32 v10, v4, v10
	v_lshlrev_b32_e32 v4, 16, v196
	v_and_b32_e32 v5, 0xffff0000, v196
	v_pk_mul_f32 v[4:5], v[4:5], v[4:5]
	s_nop 0
	v_add_f32_e32 v4, v4, v5
	v_add_f32_e32 v12, v10, v4
	v_and_b32_e32 v10, 0xffff0000, v197
	v_lshlrev_b32_e32 v5, 16, v198
	v_lshlrev_b32_e32 v4, 16, v197
	v_pk_mul_f32 v[6:7], v[10:11], v[10:11]
	s_nop 0
	v_pk_fma_f32 v[4:5], v[4:5], v[4:5], v[6:7]
	s_nop 0
	v_add_f32_e32 v4, v4, v12
	v_add_f32_e32 v6, v5, v4
	v_lshlrev_b32_e32 v4, 16, v199
	v_and_b32_e32 v5, 0xffff0000, v199
	v_pk_mul_f32 v[4:5], v[4:5], v[4:5]
	s_nop 0
	v_add_f32_e32 v4, v4, v5
	v_add_f32_e32 v4, v4, v6
	global_load_dwordx4 v[196:199], v[2:3], off offset:208
	global_load_dwordx4 v[200:203], v[2:3], off offset:192
	global_load_dwordx4 v[204:207], v[2:3], off offset:176
	global_load_dwordx4 v[236:239], v[2:3], off offset:160
	s_waitcnt vmcnt(4)
	v_lshlrev_b32_e32 v22, 16, v192
	v_and_b32_e32 v23, 0xffff0000, v192
	v_pk_mul_f32 v[22:23], v[22:23], v[22:23]
	s_nop 0
	v_add_f32_e32 v5, v22, v23
	v_and_b32_e32 v23, 0xffff0000, v194
	v_and_b32_e32 v22, 0xffff0000, v193
	v_add_f32_e32 v24, v4, v5
	v_lshlrev_b32_e32 v5, 16, v194
	v_lshlrev_b32_e32 v4, 16, v193
	v_pk_mul_f32 v[18:19], v[22:23], v[22:23]
	s_nop 0
	v_pk_fma_f32 v[4:5], v[4:5], v[4:5], v[18:19]
	v_and_b32_e32 v19, 0xffff0000, v190
	v_add_f32_e32 v4, v4, v24
	v_add_f32_e32 v18, v5, v4
	v_lshlrev_b32_e32 v4, 16, v195
	v_and_b32_e32 v5, 0xffff0000, v195
	v_pk_mul_f32 v[4:5], v[4:5], v[4:5]
	s_nop 0
	v_add_f32_e32 v4, v4, v5
	v_add_f32_e32 v18, v4, v18
	v_lshlrev_b32_e32 v4, 16, v188
	v_and_b32_e32 v5, 0xffff0000, v188
	v_pk_mul_f32 v[4:5], v[4:5], v[4:5]
	s_nop 0
	v_add_f32_e32 v4, v4, v5
	v_add_f32_e32 v20, v18, v4
	v_and_b32_e32 v18, 0xffff0000, v189
	v_lshlrev_b32_e32 v5, 16, v190
	v_lshlrev_b32_e32 v4, 16, v189
	v_pk_mul_f32 v[14:15], v[18:19], v[18:19]
	s_nop 0
	v_pk_fma_f32 v[4:5], v[4:5], v[4:5], v[14:15]
	v_and_b32_e32 v15, 0xffff0000, v186
	v_add_f32_e32 v4, v4, v20
	v_add_f32_e32 v14, v5, v4
	v_lshlrev_b32_e32 v4, 16, v191
	v_and_b32_e32 v5, 0xffff0000, v191
	v_pk_mul_f32 v[4:5], v[4:5], v[4:5]
	s_nop 0
	v_add_f32_e32 v4, v4, v5
	v_add_f32_e32 v14, v4, v14
	v_lshlrev_b32_e32 v4, 16, v184
	v_and_b32_e32 v5, 0xffff0000, v184
	v_pk_mul_f32 v[4:5], v[4:5], v[4:5]
	s_nop 0
	v_add_f32_e32 v4, v4, v5
	v_add_f32_e32 v16, v14, v4
	v_and_b32_e32 v14, 0xffff0000, v185
	v_lshlrev_b32_e32 v5, 16, v186
	v_lshlrev_b32_e32 v4, 16, v185
	v_pk_mul_f32 v[10:11], v[14:15], v[14:15]
	s_nop 0
	v_pk_fma_f32 v[4:5], v[4:5], v[4:5], v[10:11]
	v_and_b32_e32 v11, 0xffff0000, v182
	v_add_f32_e32 v4, v4, v16
	v_add_f32_e32 v10, v5, v4
	v_lshlrev_b32_e32 v4, 16, v187
	v_and_b32_e32 v5, 0xffff0000, v187
	v_pk_mul_f32 v[4:5], v[4:5], v[4:5]
	s_nop 0
	v_add_f32_e32 v4, v4, v5
	v_add_f32_e32 v10, v4, v10
	v_lshlrev_b32_e32 v4, 16, v180
	v_and_b32_e32 v5, 0xffff0000, v180
	v_pk_mul_f32 v[4:5], v[4:5], v[4:5]
	s_nop 0
	v_add_f32_e32 v4, v4, v5
	v_add_f32_e32 v12, v10, v4
	v_and_b32_e32 v10, 0xffff0000, v181
	v_lshlrev_b32_e32 v5, 16, v182
	v_lshlrev_b32_e32 v4, 16, v181
	v_pk_mul_f32 v[6:7], v[10:11], v[10:11]
	s_nop 0
	v_pk_fma_f32 v[4:5], v[4:5], v[4:5], v[6:7]
	s_nop 0
	v_add_f32_e32 v4, v4, v12
	v_add_f32_e32 v6, v5, v4
	v_lshlrev_b32_e32 v4, 16, v183
	v_and_b32_e32 v5, 0xffff0000, v183
	v_pk_mul_f32 v[4:5], v[4:5], v[4:5]
	s_nop 0
	v_add_f32_e32 v4, v4, v5
	v_add_f32_e32 v4, v4, v6
	s_waitcnt vmcnt(0)
	v_lshlrev_b32_e32 v22, 16, v236
	v_and_b32_e32 v23, 0xffff0000, v236
	v_pk_mul_f32 v[22:23], v[22:23], v[22:23]
	s_nop 0
	v_add_f32_e32 v5, v22, v23
	v_and_b32_e32 v23, 0xffff0000, v238
	v_and_b32_e32 v22, 0xffff0000, v237
	v_add_f32_e32 v24, v4, v5
	v_lshlrev_b32_e32 v5, 16, v238
	v_lshlrev_b32_e32 v4, 16, v237
	v_pk_mul_f32 v[18:19], v[22:23], v[22:23]
	s_nop 0
	v_pk_fma_f32 v[4:5], v[4:5], v[4:5], v[18:19]
	v_and_b32_e32 v19, 0xffff0000, v206
	v_add_f32_e32 v4, v4, v24
	v_add_f32_e32 v18, v5, v4
	v_lshlrev_b32_e32 v4, 16, v239
	v_and_b32_e32 v5, 0xffff0000, v239
	v_pk_mul_f32 v[4:5], v[4:5], v[4:5]
	s_nop 0
	v_add_f32_e32 v4, v4, v5
	v_add_f32_e32 v18, v4, v18
	v_lshlrev_b32_e32 v4, 16, v204
	v_and_b32_e32 v5, 0xffff0000, v204
	v_pk_mul_f32 v[4:5], v[4:5], v[4:5]
	s_nop 0
	v_add_f32_e32 v4, v4, v5
	v_add_f32_e32 v20, v18, v4
	v_and_b32_e32 v18, 0xffff0000, v205
	v_lshlrev_b32_e32 v5, 16, v206
	v_lshlrev_b32_e32 v4, 16, v205
	v_pk_mul_f32 v[14:15], v[18:19], v[18:19]
	s_nop 0
	v_pk_fma_f32 v[4:5], v[4:5], v[4:5], v[14:15]
	v_and_b32_e32 v15, 0xffff0000, v202
	v_add_f32_e32 v4, v4, v20
	v_add_f32_e32 v14, v5, v4
	v_lshlrev_b32_e32 v4, 16, v207
	v_and_b32_e32 v5, 0xffff0000, v207
	v_pk_mul_f32 v[4:5], v[4:5], v[4:5]
	s_nop 0
	v_add_f32_e32 v4, v4, v5
	v_add_f32_e32 v14, v4, v14
	v_lshlrev_b32_e32 v4, 16, v200
	v_and_b32_e32 v5, 0xffff0000, v200
	v_pk_mul_f32 v[4:5], v[4:5], v[4:5]
	s_nop 0
	v_add_f32_e32 v4, v4, v5
	v_add_f32_e32 v16, v14, v4
	v_and_b32_e32 v14, 0xffff0000, v201
	v_lshlrev_b32_e32 v5, 16, v202
	v_lshlrev_b32_e32 v4, 16, v201
	v_pk_mul_f32 v[10:11], v[14:15], v[14:15]
	s_nop 0
	v_pk_fma_f32 v[4:5], v[4:5], v[4:5], v[10:11]
	v_and_b32_e32 v11, 0xffff0000, v198
	v_add_f32_e32 v4, v4, v16
	v_add_f32_e32 v10, v5, v4
	v_lshlrev_b32_e32 v4, 16, v203
	v_and_b32_e32 v5, 0xffff0000, v203
	v_pk_mul_f32 v[4:5], v[4:5], v[4:5]
	s_nop 0
	v_add_f32_e32 v4, v4, v5
	v_add_f32_e32 v10, v4, v10
	v_lshlrev_b32_e32 v4, 16, v196
	v_and_b32_e32 v5, 0xffff0000, v196
	v_pk_mul_f32 v[4:5], v[4:5], v[4:5]
	s_nop 0
	v_add_f32_e32 v4, v4, v5
	v_add_f32_e32 v12, v10, v4
	v_and_b32_e32 v10, 0xffff0000, v197
	v_lshlrev_b32_e32 v5, 16, v198
	v_lshlrev_b32_e32 v4, 16, v197
	v_pk_mul_f32 v[6:7], v[10:11], v[10:11]
	s_nop 0
	v_pk_fma_f32 v[4:5], v[4:5], v[4:5], v[6:7]
	s_nop 0
	v_add_f32_e32 v4, v4, v12
	v_add_f32_e32 v6, v5, v4
	v_lshlrev_b32_e32 v4, 16, v199
	v_and_b32_e32 v5, 0xffff0000, v199
	v_pk_mul_f32 v[4:5], v[4:5], v[4:5]
	s_nop 0
	v_add_f32_e32 v4, v4, v5
	v_add_f32_e32 v4, v4, v6
	v_and_b32_e32 v3, 64, v228
	v_xor_b32_e32 v2, 1, v228
	v_add_u32_e32 v3, 64, v3
	v_cmp_lt_i32_e32 vcc, v2, v3
	s_nop 1
	v_cndmask_b32_e32 v2, v228, v2, vcc
	v_lshlrev_b32_e32 v2, 2, v2
	ds_bpermute_b32 v2, v2, v4
	v_cmp_eq_u32_e32 vcc, 0, v0
	s_and_saveexec_b64 s[4:5], vcc
	s_cbranch_execz .LBB0_595
	s_waitcnt lgkmcnt(0)
	v_add_f32_e32 v0, v4, v2
	v_fmamk_f32 v0, v0, 0x3b800000, v224
	v_mul_f32_e32 v2, 0x4b800000, v0
	v_cmp_gt_f32_e32 vcc, s59, v0
	s_nop 1
	v_cndmask_b32_e32 v0, v0, v2, vcc
	v_rsq_f32_e32 v0, v0
	s_nop 0
	v_mul_f32_e32 v2, 0x45800000, v0
	v_cndmask_b32_e32 v0, v0, v2, vcc
	v_mov_b32_e32 v2, 0x12000
	v_lshl_add_u32 v2, v66, 2, v2
	ds_write_b32 v2, v0
